# adds gate-GEMV next-row prefetch in mlstm_pre, L2 prefetch of next value tile, barrier sunk below small loads in mLSTM scan
# baseline (speedup 1.0000x reference)
.LBB0_398:
	s_lshl_b32 s0, s5, 4
	s_and_b32 s8, s0, 0xfffff000
	s_lshl_b32 s0, s89, 4
	s_and_b32 s97, s89, 3
	s_and_b32 s9, s0, 0xfc0
	s_lshl_b32 s0, s97, 13
	v_lshl_add_u64 v[120:121], v[130:131], 0, s[0:1]
	s_mov_b64 s[14:15], 0x1000
	s_waitcnt lgkmcnt(1)
	v_add_co_u32_e32 v2, vcc, 0x1000, v120
	v_lshl_add_u64 v[0:1], v[120:121], 0, s[14:15]
	s_waitcnt lgkmcnt(0)
	v_addc_co_u32_e32 v3, vcc, 0, v121, vcc
	s_mov_b64 s[14:15], 0x1800
	global_load_dwordx4 v[52:55], v[120:121], off
	global_load_dwordx4 v[44:47], v[120:121], off offset:16
	global_load_dwordx4 v[36:39], v[120:121], off offset:2048
	global_load_dwordx4 v[32:35], v[120:121], off offset:2064
	global_load_dwordx4 v[48:51], v[2:3], off
	global_load_dwordx4 v[40:43], v[0:1], off offset:16
	v_lshl_add_u64 v[0:1], v[120:121], 0, s[14:15]
	s_mov_b64 s[14:15], 0x8000
	global_load_dwordx4 v[60:63], v[2:3], off offset:2048
	global_load_dwordx4 v[56:59], v[0:1], off offset:16
	v_lshl_add_u64 v[0:1], v[120:121], 0, s[14:15]
	v_add_co_u32_e32 v2, vcc, 0x8000, v120
	s_mov_b64 s[14:15], 0x8800
	s_nop 0
	v_addc_co_u32_e32 v3, vcc, 0, v121, vcc
	v_lshl_add_u64 v[4:5], v[120:121], 0, s[14:15]
	s_mov_b64 s[14:15], 0x9000
	v_lshl_add_u64 v[12:13], v[120:121], 0, s[14:15]
	v_add_co_u32_e32 v16, vcc, 0x9000, v120
	s_mov_b64 s[14:15], 0x9800
	s_nop 0
	v_addc_co_u32_e32 v17, vcc, 0, v121, vcc
	v_lshl_add_u64 v[18:19], v[120:121], 0, s[14:15]
	global_load_dwordx4 v[68:71], v[2:3], off
	global_load_dwordx4 v[64:67], v[0:1], off offset:16
	s_nop 0
	global_load_dwordx4 v[0:3], v[2:3], off offset:2048
	s_nop 0
	global_load_dwordx4 v[4:7], v[4:5], off offset:16
	s_nop 0
	global_load_dwordx4 v[8:11], v[16:17], off
	s_nop 0
	global_load_dwordx4 v[12:15], v[12:13], off offset:16
	s_nop 0
	global_load_dwordx4 v[76:79], v[16:17], off offset:2048
	global_load_dwordx4 v[72:75], v[18:19], off offset:16
	s_mov_b64 s[14:15], 0x10000
	v_add_co_u32_e32 v18, vcc, 0x10000, v120
	v_lshl_add_u64 v[16:17], v[120:121], 0, s[14:15]
	s_nop 0
	v_addc_co_u32_e32 v19, vcc, 0, v121, vcc
	s_mov_b64 s[14:15], 0x10800
	global_load_dwordx4 v[104:107], v[18:19], off
	global_load_dwordx4 v[100:103], v[16:17], off offset:16
	v_lshl_add_u64 v[16:17], v[120:121], 0, s[14:15]
	global_load_dwordx4 v[108:111], v[18:19], off offset:2048
	global_load_dwordx4 v[96:99], v[16:17], off offset:16
	s_mov_b64 s[14:15], 0x11000
	v_add_co_u32_e32 v18, vcc, 0x11000, v120
	v_lshl_add_u64 v[16:17], v[120:121], 0, s[14:15]
	s_nop 0
	v_addc_co_u32_e32 v19, vcc, 0, v121, vcc
	s_mov_b64 s[14:15], 0x11800
	global_load_dwordx4 v[92:95], v[18:19], off
	global_load_dwordx4 v[80:83], v[16:17], off offset:16
	v_lshl_add_u64 v[16:17], v[120:121], 0, s[14:15]
	s_mov_b64 s[14:15], 0x18000
	global_load_dwordx4 v[88:91], v[18:19], off offset:2048
	global_load_dwordx4 v[84:87], v[16:17], off offset:16
	v_lshl_add_u64 v[16:17], v[120:121], 0, s[14:15]
	v_add_co_u32_e32 v18, vcc, 0x18000, v120
	s_mov_b64 s[14:15], 0x18800
	s_nop 0
	v_addc_co_u32_e32 v19, vcc, 0, v121, vcc
	v_lshl_add_u64 v[20:21], v[120:121], 0, s[14:15]
	s_mov_b64 s[14:15], 0x19000
	v_lshl_add_u64 v[28:29], v[120:121], 0, s[14:15]
	v_add_co_u32_e32 v122, vcc, 0x19000, v120
	s_mov_b64 s[14:15], 0x19800
	s_nop 0
	v_addc_co_u32_e32 v123, vcc, 0, v121, vcc
	v_lshl_add_u64 v[124:125], v[120:121], 0, s[14:15]
	global_load_dwordx4 v[116:119], v[18:19], off
	global_load_dwordx4 v[112:115], v[16:17], off offset:16
	s_nop 0
	global_load_dwordx4 v[16:19], v[18:19], off offset:2048
	s_nop 0
	global_load_dwordx4 v[20:23], v[20:21], off offset:16
	s_nop 0
	global_load_dwordx4 v[24:27], v[122:123], off
	s_nop 0
	global_load_dwordx4 v[28:31], v[28:29], off offset:16
	s_nop 0
	global_load_dwordx4 v[120:123], v[122:123], off offset:2048
	s_nop 0
	global_load_dwordx4 v[124:127], v[124:125], off offset:16
	v_cmp_lt_i32_e32 vcc, v213, v212
	v_readfirstlane_b32 s95, v221
	s_lshr_b32 s12, s95, 6
	v_cndmask_b32_e32 v128, v210, v213, vcc
	v_cmp_lt_i32_e32 vcc, v214, v212
	s_lshl_b32 s0, s12, 3
	s_or_b32 s8, s8, s9
	v_cndmask_b32_e32 v141, v210, v214, vcc
	v_cmp_lt_i32_e32 vcc, v215, v212
	s_lshl_b32 s12, s12, 7
	s_add_i32 s0, s8, s0
	v_cndmask_b32_e32 v142, v210, v215, vcc
	v_cmp_lt_i32_e32 vcc, v216, v212
	v_lshlrev_b32_e32 v224, 2, v142
	s_add_i32 s12, s12, 0
	v_cndmask_b32_e32 v142, v210, v216, vcc
	v_cmp_lt_i32_e32 vcc, v217, v212
	v_lshlrev_b32_e32 v225, 2, v142
	s_lshl_b64 s[8:9], s[0:1], 12
	v_cndmask_b32_e32 v142, v210, v217, vcc
	v_cmp_lt_i32_e32 vcc, v218, v212
	v_lshlrev_b32_e32 v226, 2, v142
	v_lshlrev_b32_e32 v128, 2, v128
	v_cndmask_b32_e32 v142, v210, v218, vcc
	v_lshlrev_b32_e32 v141, 2, v141
	v_lshlrev_b32_e32 v227, 2, v142
	s_waitcnt vmcnt(25)
	v_mov_b32_e32 v143, v61
	v_mov_b32_e32 v145, v63
	s_waitcnt vmcnt(24)
	v_mov_b32_e32 v147, v57
	v_mov_b32_e32 v149, v59
	v_mov_b32_e32 v199, v45
	v_mov_b32_e32 v201, v47
	v_mov_b32_e32 v203, v53
	v_mov_b32_e32 v205, v55
	s_add_i32 s12, s12, 0x10800
	s_waitcnt vmcnt(23)
	v_mov_b32_e32 v202, v68
	s_waitcnt vmcnt(21)
	v_pk_mov_b32 v[194:195], v[2:3], v[38:39] op_sel:[1,0]
	s_waitcnt vmcnt(19)
	v_pk_mov_b32 v[186:187], v[10:11], v[50:51] op_sel:[1,0]
	s_waitcnt vmcnt(17)
	v_mov_b32_e32 v142, v76
	v_mov_b32_e32 v144, v78
	s_waitcnt vmcnt(16)
	v_mov_b32_e32 v146, v72
	v_mov_b32_e32 v148, v74
	v_pk_mov_b32 v[182:183], v[14:15], v[42:43] op_sel:[1,0]
	v_pk_mov_b32 v[184:185], v[12:13], v[40:41] op_sel:[1,0]
	v_pk_mov_b32 v[188:189], v[8:9], v[48:49] op_sel:[1,0]
	v_pk_mov_b32 v[190:191], v[6:7], v[34:35] op_sel:[1,0]
	s_waitcnt vmcnt(15)
	v_mov_b32_e32 v178, v104
	s_waitcnt vmcnt(14)
	v_mov_b32_e32 v174, v100
	v_mov_b32_e32 v176, v102
	v_mov_b32_e32 v180, v106
	v_pk_mov_b32 v[192:193], v[4:5], v[32:33] op_sel:[1,0]
	v_pk_mov_b32 v[196:197], v[0:1], v[36:37] op_sel:[1,0]
	v_mov_b32_e32 v198, v64
	v_mov_b32_e32 v200, v66
	v_mov_b32_e32 v204, v70
	v_pk_mov_b32 v[52:53], v[68:69], v[52:53] op_sel:[1,0]
	v_pk_mov_b32 v[54:55], v[70:71], v[54:55] op_sel:[1,0]
	v_pk_mov_b32 v[44:45], v[64:65], v[44:45] op_sel:[1,0]
	v_pk_mov_b32 v[46:47], v[66:67], v[46:47] op_sel:[1,0]
	s_waitcnt vmcnt(9)
	v_mov_b32_e32 v151, v89
	v_mov_b32_e32 v153, v91
	s_waitcnt vmcnt(8)
	v_mov_b32_e32 v155, v85
	v_mov_b32_e32 v157, v87
	v_mov_b32_e32 v1, v37
	v_mov_b32_e32 v3, v39
	v_mov_b32_e32 v5, v33
	v_mov_b32_e32 v7, v35
	v_mov_b32_e32 v9, v49
	v_mov_b32_e32 v11, v51
	v_mov_b32_e32 v13, v41
	v_mov_b32_e32 v15, v43
	v_pk_mov_b32 v[32:33], v[76:77], v[60:61] op_sel:[1,0]
	v_pk_mov_b32 v[34:35], v[78:79], v[62:63] op_sel:[1,0]
	v_pk_mov_b32 v[36:37], v[72:73], v[56:57] op_sel:[1,0]
	v_pk_mov_b32 v[38:39], v[74:75], v[58:59] op_sel:[1,0]
	s_waitcnt vmcnt(7)
	v_mov_b32_e32 v179, v117
	s_waitcnt vmcnt(5)
	v_pk_mov_b32 v[170:171], v[18:19], v[110:111] op_sel:[1,0]
	s_waitcnt vmcnt(3)
	v_pk_mov_b32 v[162:163], v[26:27], v[94:95] op_sel:[1,0]
	s_waitcnt vmcnt(1)
	v_mov_b32_e32 v150, v120
	v_mov_b32_e32 v152, v122
	s_waitcnt vmcnt(0)
	v_mov_b32_e32 v154, v124
	v_mov_b32_e32 v156, v126
	v_pk_mov_b32 v[158:159], v[30:31], v[82:83] op_sel:[1,0]
	v_pk_mov_b32 v[160:161], v[28:29], v[80:81] op_sel:[1,0]
	v_pk_mov_b32 v[164:165], v[24:25], v[92:93] op_sel:[1,0]
	v_pk_mov_b32 v[166:167], v[22:23], v[98:99] op_sel:[1,0]
	v_pk_mov_b32 v[168:169], v[20:21], v[96:97] op_sel:[1,0]
	v_pk_mov_b32 v[172:173], v[16:17], v[108:109] op_sel:[1,0]
	v_mov_b32_e32 v175, v113
	v_mov_b32_e32 v177, v115
	v_mov_b32_e32 v181, v119
	v_pk_mov_b32 v[68:69], v[104:105], v[116:117] op_sel:[1,0]
	v_pk_mov_b32 v[70:71], v[106:107], v[118:119] op_sel:[1,0]
	v_pk_mov_b32 v[64:65], v[100:101], v[112:113] op_sel:[1,0]
	v_pk_mov_b32 v[66:67], v[102:103], v[114:115] op_sel:[1,0]
	v_mov_b32_e32 v17, v109
	v_mov_b32_e32 v19, v111
	v_mov_b32_e32 v21, v97
	v_mov_b32_e32 v23, v99
	v_mov_b32_e32 v25, v93
	v_mov_b32_e32 v27, v95
	v_mov_b32_e32 v29, v81
	v_mov_b32_e32 v31, v83
	v_pk_mov_b32 v[40:41], v[120:121], v[88:89] op_sel:[1,0]
	v_pk_mov_b32 v[42:43], v[122:123], v[90:91] op_sel:[1,0]
	v_pk_mov_b32 v[48:49], v[124:125], v[84:85] op_sel:[1,0]
	v_pk_mov_b32 v[50:51], v[126:127], v[86:87] op_sel:[1,0]
	v_lshl_add_u64 v[56:57], v[138:139], 0, s[8:9]
	s_mov_b64 s[24:25], 0
	v_lshl_add_u64 v[246:247], v[56:57], 0, s[24:25]
	s_nop 0
	v_add_co_u32_e32 v246, vcc, 0xb100000, v246
	s_nop 1
	v_addc_co_u32_e32 v247, vcc, 0, v247, vcc
	global_load_dwordx4 v[230:233], v[246:247], off
	global_load_dwordx4 v[234:237], v[246:247], off offset:1024
	global_load_dwordx4 v[238:241], v[246:247], off offset:2048
	global_load_dwordx4 v[242:245], v[246:247], off offset:3072
	s_branch .LBB0_400

.LBB0_400:
	s_waitcnt lgkmcnt(0)
	s_waitcnt vmcnt(0)
	v_mov_b32_e32 v58, v230
	v_mov_b32_e32 v59, v231
	v_mov_b32_e32 v60, v232
	v_mov_b32_e32 v61, v233
	v_mov_b32_e32 v72, v234
	v_mov_b32_e32 v73, v235
	v_mov_b32_e32 v74, v236
	v_mov_b32_e32 v75, v237
	v_mov_b32_e32 v76, v238
	v_mov_b32_e32 v77, v239
	v_mov_b32_e32 v78, v240
	v_mov_b32_e32 v79, v241
	v_mov_b32_e32 v80, v242
	v_mov_b32_e32 v81, v243
	v_mov_b32_e32 v82, v244
	v_mov_b32_e32 v83, v245
	s_cmpk_eq_u32 s24, 0x7000
	s_cbranch_scc1 .Lgate_nopf
	v_lshl_add_u64 v[246:247], v[56:57], 0, s[24:25]
	s_nop 0
	v_add_co_u32_e32 v246, vcc, 0xb101000, v246
	s_nop 1
	v_addc_co_u32_e32 v247, vcc, 0, v247, vcc
	global_load_dwordx4 v[230:233], v[246:247], off
	global_load_dwordx4 v[234:237], v[246:247], off offset:1024
	global_load_dwordx4 v[238:241], v[246:247], off offset:2048
	global_load_dwordx4 v[242:245], v[246:247], off offset:3072
.Lgate_nopf:
	v_and_b32_e32 v63, 0xffff0000, v58
	v_and_b32_e32 v85, 0xffff0000, v59
	v_and_b32_e32 v89, 0xffff0000, v60
	v_and_b32_e32 v91, 0xffff0000, v61
	v_and_b32_e32 v94, 0xffff0000, v72
	v_and_b32_e32 v98, 0xffff0000, v73
	v_and_b32_e32 v100, 0xffff0000, v74
	v_and_b32_e32 v104, 0xffff0000, v75
	v_and_b32_e32 v62, 16, v58
	v_lshlrev_b32_e32 v58, 16, v58
	v_and_b32_e32 v84, 16, v59
	v_lshlrev_b32_e32 v86, 16, v59
	v_and_b32_e32 v88, 16, v60
	v_lshlrev_b32_e32 v60, 16, v60
	v_and_b32_e32 v90, 16, v61
	v_lshlrev_b32_e32 v92, 16, v61
	v_and_b32_e32 v95, 16, v72
	v_lshlrev_b32_e32 v97, 16, v72
	v_and_b32_e32 v99, 16, v73
	v_lshlrev_b32_e32 v73, 16, v73
	v_and_b32_e32 v101, 16, v74
	v_lshlrev_b32_e32 v103, 16, v74
	v_and_b32_e32 v105, 16, v75
	v_lshlrev_b32_e32 v75, 16, v75
	v_mov_b32_e32 v59, v63
	v_mov_b32_e32 v87, v85
	v_mov_b32_e32 v61, v89
	v_mov_b32_e32 v93, v91
	v_mov_b32_e32 v96, v94
	v_mov_b32_e32 v72, v98
	v_mov_b32_e32 v102, v100
	v_mov_b32_e32 v74, v104
	v_pk_mul_f32 v[110:111], v[202:203], v[58:59]
	v_pk_mov_b32 v[62:63], v[62:63], v[58:59] op_sel:[1,0]
	v_pk_mul_f32 v[112:113], v[204:205], v[86:87]
	v_pk_mov_b32 v[84:85], v[84:85], v[86:87] op_sel:[1,0]
	v_pk_mul_f32 v[114:115], v[198:199], v[60:61]
	v_pk_mov_b32 v[88:89], v[88:89], v[60:61] op_sel:[1,0]
	v_pk_mul_f32 v[116:117], v[200:201], v[92:93]
	v_pk_mov_b32 v[90:91], v[90:91], v[92:93] op_sel:[1,0]
	v_pk_mov_b32 v[94:95], v[96:97], v[94:95] op_sel:[1,0]
	v_pk_mov_b32 v[98:99], v[72:73], v[98:99] op_sel:[1,0]
	v_pk_mov_b32 v[100:101], v[102:103], v[100:101] op_sel:[1,0]
	v_pk_mov_b32 v[104:105], v[74:75], v[104:105] op_sel:[1,0]
	v_pk_fma_f32 v[110:111], v[52:53], v[62:63], v[110:111]
	v_pk_fma_f32 v[112:113], v[54:55], v[84:85], v[112:113]
	v_pk_mul_f32 v[62:63], v[68:69], v[62:63]
	v_pk_mul_f32 v[84:85], v[70:71], v[84:85]
	v_pk_fma_f32 v[114:115], v[44:45], v[88:89], v[114:115]
	v_pk_fma_f32 v[116:117], v[46:47], v[90:91], v[116:117]
	v_pk_mul_f32 v[88:89], v[64:65], v[88:89]
	v_pk_mul_f32 v[90:91], v[66:67], v[90:91]
	v_pk_mul_f32 v[118:119], v[0:1], v[94:95]
	v_pk_mul_f32 v[94:95], v[16:17], v[94:95]
	v_pk_mul_f32 v[120:121], v[2:3], v[98:99]
	v_pk_mul_f32 v[98:99], v[18:19], v[98:99]
	v_pk_mul_f32 v[122:123], v[4:5], v[100:101]
	v_pk_mul_f32 v[124:125], v[6:7], v[104:105]
	v_pk_mul_f32 v[100:101], v[20:21], v[100:101]
	v_pk_add_f32 v[110:111], v[110:111], v[112:113]
	v_pk_fma_f32 v[58:59], v[178:179], v[58:59], v[62:63]
	v_pk_fma_f32 v[62:63], v[180:181], v[86:87], v[84:85]
	v_pk_add_f32 v[84:85], v[114:115], v[116:117]
	v_pk_fma_f32 v[60:61], v[174:175], v[60:61], v[88:89]
	v_pk_fma_f32 v[86:87], v[176:177], v[92:93], v[90:91]
	v_pk_fma_f32 v[88:89], v[196:197], v[96:97], v[118:119]
	v_pk_fma_f32 v[90:91], v[172:173], v[96:97], v[94:95]
	v_pk_fma_f32 v[92:93], v[194:195], v[72:73], v[120:121]
	v_pk_fma_f32 v[72:73], v[170:171], v[72:73], v[98:99]
	v_pk_fma_f32 v[94:95], v[192:193], v[102:103], v[122:123]
	v_pk_fma_f32 v[98:99], v[190:191], v[74:75], v[124:125]
	v_and_b32_e32 v106, 0xffff0000, v76
	v_pk_mul_f32 v[104:105], v[22:23], v[104:105]
	v_pk_fma_f32 v[96:97], v[168:169], v[102:103], v[100:101]
	v_and_b32_e32 v100, 0xffff0000, v77
	v_pk_add_f32 v[84:85], v[110:111], v[84:85]
	v_pk_add_f32 v[88:89], v[88:89], v[92:93]
	v_pk_add_f32 v[92:93], v[94:95], v[98:99]
	v_and_b32_e32 v107, 16, v76
	v_lshlrev_b32_e32 v109, 16, v76
	v_pk_fma_f32 v[74:75], v[166:167], v[74:75], v[104:105]
	v_pk_add_f32 v[58:59], v[58:59], v[62:63]
	v_pk_add_f32 v[60:61], v[60:61], v[86:87]
	v_mov_b32_e32 v108, v106
	v_and_b32_e32 v101, 16, v77
	v_lshlrev_b32_e32 v77, 16, v77
	v_mov_b32_e32 v76, v100
	v_pk_add_f32 v[84:85], v[84:85], 0 op_sel_hi:[1,0]
	v_pk_add_f32 v[88:89], v[88:89], v[92:93]
	v_pk_mul_f32 v[62:63], v[188:189], v[108:109]
	v_pk_mul_f32 v[102:103], v[186:187], v[76:77]
	v_pk_mul_f32 v[104:105], v[162:163], v[76:77]
	v_and_b32_e32 v112, 0xffff0000, v78
	v_and_b32_e32 v120, 0xffff0000, v79
	v_pk_add_f32 v[84:85], v[84:85], v[88:89]
	v_pk_mov_b32 v[88:89], v[108:109], v[106:107] op_sel:[1,0]
	v_pk_mov_b32 v[76:77], v[76:77], v[100:101] op_sel:[1,0]
	v_pk_add_f32 v[58:59], v[58:59], v[60:61]
	v_pk_add_f32 v[60:61], v[90:91], v[72:73]
	v_pk_add_f32 v[72:73], v[96:97], v[74:75]
	v_pk_mul_f32 v[86:87], v[164:165], v[108:109]
	v_and_b32_e32 v113, 16, v78
	v_lshlrev_b32_e32 v115, 16, v78
	v_mov_b32_e32 v114, v112
	v_and_b32_e32 v121, 16, v79
	v_lshlrev_b32_e32 v79, 16, v79
	v_mov_b32_e32 v78, v120
	v_pk_fma_f32 v[62:63], v[8:9], v[88:89], v[62:63]
	v_pk_fma_f32 v[92:93], v[10:11], v[76:77], v[102:103]
	v_pk_add_f32 v[58:59], v[58:59], 0 op_sel_hi:[1,0]
	v_pk_add_f32 v[60:61], v[60:61], v[72:73]
	v_pk_mul_f32 v[116:117], v[184:185], v[114:115]
	v_pk_mul_f32 v[118:119], v[160:161], v[114:115]
	v_pk_mul_f32 v[122:123], v[182:183], v[78:79]
	v_pk_mul_f32 v[124:125], v[158:159], v[78:79]
	v_pk_add_f32 v[62:63], v[62:63], v[92:93]
	v_pk_mov_b32 v[92:93], v[114:115], v[112:113] op_sel:[1,0]
	v_pk_mov_b32 v[78:79], v[78:79], v[120:121] op_sel:[1,0]
	v_pk_add_f32 v[58:59], v[58:59], v[60:61] op_sel:[1,0] op_sel_hi:[0,1]
	v_pk_fma_f32 v[60:61], v[24:25], v[88:89], v[86:87]
	v_pk_fma_f32 v[72:73], v[26:27], v[76:77], v[104:105]
	v_pk_fma_f32 v[94:95], v[12:13], v[92:93], v[116:117]
	v_pk_fma_f32 v[98:99], v[14:15], v[78:79], v[122:123]
	v_pk_add_f32 v[60:61], v[60:61], v[72:73]
	v_pk_fma_f32 v[72:73], v[28:29], v[92:93], v[118:119]
	v_pk_fma_f32 v[74:75], v[30:31], v[78:79], v[124:125]
	v_pk_add_f32 v[94:95], v[94:95], v[98:99]
	v_pk_add_f32 v[72:73], v[72:73], v[74:75]
	v_lshlrev_b32_e32 v126, 16, v80
	v_and_b32_e32 v127, 0xffff0000, v80
	v_lshlrev_b32_e32 v80, 16, v81
	v_and_b32_e32 v81, 0xffff0000, v81
	v_pk_add_f32 v[62:63], v[62:63], v[94:95]
	v_pk_add_f32 v[60:61], v[60:61], v[72:73]
	v_pk_add_f32 v[62:63], v[84:85], v[62:63]
	v_pk_mul_f32 v[84:85], v[32:33], v[126:127] op_sel:[0,1] op_sel_hi:[1,0]
	v_pk_mul_f32 v[94:95], v[34:35], v[80:81] op_sel:[0,1] op_sel_hi:[1,0]
	v_pk_add_f32 v[58:59], v[58:59], v[60:61]
	v_pk_mul_f32 v[60:61], v[40:41], v[126:127] op_sel:[0,1] op_sel_hi:[1,0]
	v_pk_mul_f32 v[72:73], v[42:43], v[80:81] op_sel:[0,1] op_sel_hi:[1,0]
	v_lshlrev_b32_e32 v228, 16, v82
	v_and_b32_e32 v229, 0xffff0000, v82
	v_lshlrev_b32_e32 v82, 16, v83
	v_and_b32_e32 v83, 0xffff0000, v83
	v_pk_fma_f32 v[84:85], v[142:143], v[126:127], v[84:85]
	v_pk_fma_f32 v[94:95], v[144:145], v[80:81], v[94:95]
	v_pk_fma_f32 v[60:61], v[150:151], v[126:127], v[60:61]
	v_pk_fma_f32 v[72:73], v[152:153], v[80:81], v[72:73]
	v_pk_add_f32 v[84:85], v[84:85], v[94:95]
	v_pk_mul_f32 v[94:95], v[36:37], v[228:229] op_sel:[0,1] op_sel_hi:[1,0]
	v_pk_mul_f32 v[98:99], v[38:39], v[82:83] op_sel:[0,1] op_sel_hi:[1,0]
	v_pk_add_f32 v[60:61], v[60:61], v[72:73]
	v_pk_mul_f32 v[72:73], v[48:49], v[228:229] op_sel:[0,1] op_sel_hi:[1,0]
	v_pk_mul_f32 v[74:75], v[50:51], v[82:83] op_sel:[0,1] op_sel_hi:[1,0]
	v_pk_fma_f32 v[94:95], v[146:147], v[228:229], v[94:95]
	v_pk_fma_f32 v[98:99], v[148:149], v[82:83], v[98:99]
	v_pk_fma_f32 v[72:73], v[154:155], v[228:229], v[72:73]
	v_pk_fma_f32 v[74:75], v[156:157], v[82:83], v[74:75]
	v_pk_add_f32 v[94:95], v[94:95], v[98:99]
	v_pk_add_f32 v[72:73], v[72:73], v[74:75]
	v_pk_add_f32 v[84:85], v[84:85], v[94:95]
	v_pk_add_f32 v[60:61], v[60:61], v[72:73]
	v_pk_add_f32 v[62:63], v[62:63], v[84:85]
	v_pk_add_f32 v[58:59], v[58:59], v[60:61]
	ds_bpermute_b32 v85, v128, v63
	ds_bpermute_b32 v84, v128, v62
	ds_bpermute_b32 v61, v128, v59
	ds_bpermute_b32 v60, v128, v58
	s_waitcnt lgkmcnt(2)
	v_pk_add_f32 v[62:63], v[62:63], v[84:85]
	ds_bpermute_b32 v73, v141, v63
	s_waitcnt lgkmcnt(1)
	v_pk_add_f32 v[58:59], v[58:59], v[60:61]
	ds_bpermute_b32 v72, v141, v62
	ds_bpermute_b32 v61, v141, v59
	ds_bpermute_b32 v60, v141, v58
	s_waitcnt lgkmcnt(2)
	v_pk_add_f32 v[62:63], v[62:63], v[72:73]
	ds_bpermute_b32 v73, v224, v63
	s_waitcnt lgkmcnt(1)
	v_pk_add_f32 v[58:59], v[58:59], v[60:61]
	ds_bpermute_b32 v72, v224, v62
	ds_bpermute_b32 v61, v224, v59
	ds_bpermute_b32 v60, v224, v58
	s_waitcnt lgkmcnt(2)
	v_pk_add_f32 v[62:63], v[62:63], v[72:73]
	ds_bpermute_b32 v73, v225, v63
	s_waitcnt lgkmcnt(1)
	v_pk_add_f32 v[58:59], v[58:59], v[60:61]
	ds_bpermute_b32 v72, v225, v62
	ds_bpermute_b32 v61, v225, v59
	ds_bpermute_b32 v60, v225, v58
	s_waitcnt lgkmcnt(2)
	v_pk_add_f32 v[62:63], v[62:63], v[72:73]
	ds_bpermute_b32 v73, v226, v63
	s_waitcnt lgkmcnt(1)
	v_pk_add_f32 v[60:61], v[58:59], v[60:61]
	ds_bpermute_b32 v72, v226, v62
	ds_bpermute_b32 v75, v226, v61
	ds_bpermute_b32 v74, v226, v60
	s_waitcnt lgkmcnt(2)
	v_pk_add_f32 v[58:59], v[62:63], v[72:73]
	ds_bpermute_b32 v63, v227, v59
	s_waitcnt lgkmcnt(1)
	v_pk_add_f32 v[60:61], v[60:61], v[74:75]
	ds_bpermute_b32 v62, v227, v58
	ds_bpermute_b32 v73, v227, v61
	ds_bpermute_b32 v72, v227, v60
	s_and_saveexec_b64 s[8:9], s[2:3]
	s_cbranch_execz .LBB0_399
	s_waitcnt lgkmcnt(2)
	v_pk_add_f32 v[62:63], v[58:59], v[62:63]
	s_waitcnt lgkmcnt(0)
	v_pk_add_f32 v[72:73], v[60:61], v[72:73]
	v_mov_b32_e32 v58, v63
	v_mov_b32_e32 v59, v62
	v_mov_b32_e32 v60, v73
	v_mov_b32_e32 v61, v72
	v_mov_b32_e32 v62, s12
	ds_write_b128 v62, v[58:61]
	s_branch .LBB0_399

.LBB0_451:
	s_add_i32 s18, s34, 64
	s_sub_i32 s19, 0xfbf, s34
	s_and_b64 s[16:17], s[2:3], exec
	s_cselect_b32 s16, s18, s19
	s_ashr_i32 s17, s16, 31
	s_lshl_b64 s[16:17], s[16:17], 12
	s_sub_i32 s18, 0xfbf, s51
	s_add_i32 s19, s34, 0x41
	global_load_dword v48, v[24:25], off offset:32
	v_lshl_add_u64 v[24:25], v[64:65], 0, s[16:17]
	s_and_b64 s[16:17], s[2:3], exec
	s_cselect_b32 s16, s19, s18
	s_ashr_i32 s17, s16, 31
	s_lshl_b64 s[16:17], s[16:17], 12
	s_sub_i32 s18, 0xfbf, s63
	s_add_i32 s19, s34, 0x42
	v_lshl_add_u64 v[28:29], v[64:65], 0, s[16:17]
	s_and_b64 s[16:17], s[2:3], exec
	s_cselect_b32 s16, s19, s18
	s_ashr_i32 s17, s16, 31
	s_lshl_b64 s[16:17], s[16:17], 12
	s_sub_i32 s18, 0xfbf, s62
	s_add_i32 s19, s34, 0x43
	v_lshl_add_u64 v[30:31], v[64:65], 0, s[16:17]
	s_and_b64 s[16:17], s[2:3], exec
	s_cselect_b32 s16, s19, s18
	s_ashr_i32 s17, s16, 31
	s_lshl_b64 s[16:17], s[16:17], 12
	s_sub_i32 s18, 0xfbf, s60
	s_add_i32 s19, s34, 0x44
	v_lshl_add_u64 v[32:33], v[64:65], 0, s[16:17]
	s_and_b64 s[16:17], s[2:3], exec
	s_cselect_b32 s16, s19, s18
	s_ashr_i32 s17, s16, 31
	s_lshl_b64 s[16:17], s[16:17], 12
	s_sub_i32 s18, 0xfbf, s59
	s_add_i32 s19, s34, 0x45
	global_load_dword v151, v[24:25], off
	global_load_dword v152, v[24:25], off offset:2048
	global_load_dword v153, v[28:29], off
	global_load_dword v154, v[28:29], off offset:2048
	global_load_dword v157, v[30:31], off
	global_load_dword v158, v[30:31], off offset:2048
	global_load_dword v159, v[32:33], off
	global_load_dword v160, v[32:33], off offset:2048
	v_lshl_add_u64 v[24:25], v[64:65], 0, s[16:17]
	s_and_b64 s[16:17], s[2:3], exec
	s_cselect_b32 s16, s19, s18
	s_ashr_i32 s17, s16, 31
	s_lshl_b64 s[16:17], s[16:17], 12
	s_sub_i32 s18, 0xfbf, s58
	s_add_i32 s19, s34, 0x46
	v_lshl_add_u64 v[28:29], v[64:65], 0, s[16:17]
	s_and_b64 s[16:17], s[2:3], exec
	s_cselect_b32 s16, s19, s18
	s_ashr_i32 s17, s16, 31
	s_lshl_b64 s[16:17], s[16:17], 12
	s_sub_i32 s18, 0xfbf, s57
	s_add_i32 s19, s34, 0x47
	v_lshl_add_u64 v[30:31], v[64:65], 0, s[16:17]
	s_and_b64 s[16:17], s[2:3], exec
	s_cselect_b32 s16, s19, s18
	s_ashr_i32 s17, s16, 31
	s_lshl_b64 s[16:17], s[16:17], 12
	s_sub_i32 s18, 0xfbf, s56
	s_add_i32 s19, s34, 0x48
	v_lshl_add_u64 v[32:33], v[64:65], 0, s[16:17]
	s_and_b64 s[16:17], s[2:3], exec
	s_cselect_b32 s16, s19, s18
	s_ashr_i32 s17, s16, 31
	s_lshl_b64 s[16:17], s[16:17], 12
	s_sub_i32 s18, 0xfbf, s55
	s_add_i32 s19, s34, 0x49
	global_load_dword v161, v[24:25], off
	global_load_dword v162, v[24:25], off offset:2048
	global_load_dword v164, v[28:29], off
	global_load_dword v165, v[28:29], off offset:2048
	global_load_dword v169, v[30:31], off
	global_load_dword v171, v[30:31], off offset:2048
	global_load_dword v180, v[32:33], off
	global_load_dword v181, v[32:33], off offset:2048
	v_lshl_add_u64 v[24:25], v[64:65], 0, s[16:17]
	s_and_b64 s[16:17], s[2:3], exec
	s_cselect_b32 s16, s19, s18
	s_ashr_i32 s17, s16, 31
	s_lshl_b64 s[16:17], s[16:17], 12
	s_sub_i32 s18, 0xfbf, s54
	s_add_i32 s19, s34, 0x4a
	v_lshl_add_u64 v[28:29], v[64:65], 0, s[16:17]
	s_and_b64 s[16:17], s[2:3], exec
	s_cselect_b32 s16, s19, s18
	s_ashr_i32 s17, s16, 31
	s_lshl_b64 s[16:17], s[16:17], 12
	s_sub_i32 s18, 0xfbf, s53
	s_add_i32 s19, s34, 0x4b
	v_lshl_add_u64 v[30:31], v[64:65], 0, s[16:17]
	s_and_b64 s[16:17], s[2:3], exec
	s_cselect_b32 s16, s19, s18
	s_ashr_i32 s17, s16, 31
	s_lshl_b64 s[16:17], s[16:17], 12
	s_sub_i32 s18, 0xfbf, s52
	s_add_i32 s19, s34, 0x4c
	v_lshl_add_u64 v[32:33], v[64:65], 0, s[16:17]
	s_and_b64 s[16:17], s[2:3], exec
	s_cselect_b32 s16, s19, s18
	s_ashr_i32 s17, s16, 31
	s_lshl_b64 s[16:17], s[16:17], 12
	s_sub_i32 s18, 0xfbf, s50
	s_add_i32 s19, s34, 0x4d
	global_load_dword v190, v[24:25], off
	global_load_dword v191, v[24:25], off offset:2048
	global_load_dword v192, v[28:29], off
	global_load_dword v193, v[28:29], off offset:2048
	global_load_dword v194, v[30:31], off
	global_load_dword v195, v[30:31], off offset:2048
	global_load_dword v196, v[32:33], off
	global_load_dword v197, v[32:33], off offset:2048
	v_lshl_add_u64 v[24:25], v[64:65], 0, s[16:17]
	s_and_b64 s[16:17], s[2:3], exec
	s_cselect_b32 s16, s19, s18
	s_ashr_i32 s17, s16, 31
	s_lshl_b64 s[16:17], s[16:17], 12
	s_sub_i32 s18, 0xfbf, s48
	s_add_i32 s19, s34, 0x4e
	v_lshl_add_u64 v[28:29], v[64:65], 0, s[16:17]
	s_and_b64 s[16:17], s[2:3], exec
	s_cselect_b32 s16, s19, s18
	s_ashr_i32 s17, s16, 31
	s_lshl_b64 s[16:17], s[16:17], 12
	s_sub_i32 s18, 0xfbf, s47
	s_add_i32 s19, s34, 0x4f
	v_lshl_add_u64 v[30:31], v[64:65], 0, s[16:17]
	s_and_b64 s[16:17], s[2:3], exec
	s_cselect_b32 s16, s19, s18
	s_ashr_i32 s17, s16, 31
	s_lshl_b64 s[16:17], s[16:17], 12
	v_lshl_add_u64 v[32:33], v[64:65], 0, s[16:17]
	global_load_dword v198, v[24:25], off
	global_load_dword v199, v[24:25], off offset:2048
	global_load_dword v200, v[28:29], off
	global_load_dword v201, v[28:29], off offset:2048
	global_load_dword v202, v[30:31], off
	global_load_dword v203, v[30:31], off offset:2048
	global_load_dword v204, v[32:33], off
	global_load_dword v205, v[32:33], off offset:2048
	v_xor_b32_e32 v0, v26, v63
	v_lshl_add_u32 v166, v0, 4, v73
	v_lshlrev_b32_e32 v0, 1, v56
	v_and_b32_e32 v24, 64, v108
	v_lshl_add_u64 v[68:69], s[6:7], 0, v[0:1]
	s_and_b32 s6, s34, 48
	v_or_b32_e32 v0, s34, v50
	v_or3_b32 v27, s6, v58, v24
	s_lshr_b32 s6, s35, 1
	s_lshl_b32 s16, s46, 1
	v_mul_lo_u32 v25, v0, s78
	v_lshl_or_b32 v26, s49, 4, v50
	v_mul_lo_u32 v28, v0, s37
	v_mov_b32_e32 v0, s75
	s_and_b32 s6, s6, 0xfffffe0
	s_andn2_b32 s35, s35, 63
	v_mad_u32_u24 v168, v26, s37, v0
	v_or_b32_e32 v0, v24, v75
	v_or_b32_e32 v24, s6, v50
	s_and_b64 s[6:7], s[2:3], exec
	s_cselect_b32 s6, s77, s33
	s_cselect_b32 s7, s76, s36
	s_lshl_b64 s[4:5], s[4:5], 1
	s_add_u32 s4, s7, s4
	s_addc_u32 s5, s6, s5
	s_lshl_b32 s6, s15, 1
	s_add_u32 s4, s4, s6
	s_addc_u32 s5, s5, 0
	v_lshl_add_u32 v163, v23, 1, 0
	s_movk_i32 s17, 0x8e
	s_add_u32 s4, s4, s14
	v_mad_u32_u24 v23, v23, s17, v163
	v_lshlrev_b32_e32 v170, 2, v0
	v_xor_b32_e32 v0, s16, v63
	s_addc_u32 s5, s5, 0
	s_lshl_b32 s6, s49, 5
	v_lshl_add_u32 v173, v0, 4, v23
	v_bitop3_b32 v0, s16, v63, 1 bitop3:0x36
	s_add_u32 s4, s4, s6
	v_lshl_add_u32 v174, v0, 4, v23
	s_addc_u32 s5, s5, 0
	v_lshlrev_b32_e32 v0, 1, v50
	v_add_u32_e32 v172, s35, v78
	v_lshlrev_b32_e32 v176, 2, v27
	v_lshl_add_u64 v[70:71], s[4:5], 0, v[0:1]
	v_mul_lo_u32 v0, v24, s37
	s_mov_b32 s18, 0
	s_mov_b32 s19, 2
	v_mul_u32_u24_e32 v167, 0x210, v26
	s_mul_i32 s20, s46, 0x2100
	s_mul_i32 s21, s51, 0x210
	v_not_b32_e32 v175, v127
	v_or_b32_e32 v177, 4, v176
	v_or_b32_e32 v178, 8, v176
	v_or_b32_e32 v179, 12, v176
	v_add_u32_e32 v0, 0, v0
	s_sub_i32 s24, 0, s34
	v_or_b32_e32 v182, s6, v74
	v_add_u32_e32 v183, s34, v58
	v_subrev_u32_e32 v184, s34, v104
	v_subrev_u32_e32 v185, s34, v83
	v_subrev_u32_e32 v186, s6, v106
	s_mov_b32 s25, 62
	v_add_u32_e32 v187, v99, v25
	v_add_u32_e32 v188, v76, v28
	v_add_u32_e32 v189, v172, v85
	s_mov_b32 s26, 0
	v_mov_b32_e32 v23, v22
	v_mov_b32_e32 v24, v22
	v_mov_b32_e32 v25, v22
	v_mov_b32_e32 v30, v22
	v_mov_b32_e32 v31, v22
	v_mov_b32_e32 v32, v22
	v_mov_b32_e32 v33, v22
	v_mov_b32_e32 v26, v22
	v_mov_b32_e32 v27, v22
	v_mov_b32_e32 v28, v22
	v_mov_b32_e32 v29, v22
	v_mov_b32_e32 v34, v22
	v_mov_b32_e32 v35, v22
	v_mov_b32_e32 v36, v22
	v_mov_b32_e32 v37, v22
	v_mov_b32_e32 v38, v22
	v_mov_b32_e32 v39, v22
	v_mov_b32_e32 v40, v22
	v_mov_b32_e32 v41, v22
	v_mov_b32_e32 v42, v22
	v_mov_b32_e32 v43, v22
	v_mov_b32_e32 v44, v22
	v_mov_b32_e32 v45, v22
	v_readfirstlane_b32 s58, v64
	v_readfirstlane_b32 s59, v65
	s_lshr_b32 s36, s35, 6
	s_and_b32 s36, s36, 1
	s_lshl_b32 s36, s36, 8
	s_sub_u32 s58, s58, s36
	s_subb_u32 s59, s59, 0
	v_lshlrev_b32_e32 v89, 2, v220
	v_add_u32_e32 v89, s36, v89
	s_cmp_eq_u32 s61, 0
	s_cselect_b32 s57, 0, -1
	s_xor_b32 s56, s57, 0x40000
	s_sub_i32 s56, s56, s57
	s_xor_b32 s36, s57, 0x2000
	s_sub_i32 s36, s36, s57
	s_and_b32 s37, s57, 0xe000
	s_and_b32 s40, s57, 0x1000
	s_andn2_b32 s41, 0x1000, s57
	s_add_i32 s38, s34, 0x80
	s_sub_i32 s39, 0xf70, s34
	s_cmp_eq_u32 s61, 0
	s_cselect_b32 s38, s38, s39
	s_lshl_b32 s38, s38, 12
	s_add_u32 s58, s58, s38
	s_addc_u32 s59, s59, 0
	s_add_u32 s52, s58, s40
	s_addc_u32 s53, s59, 0
	s_add_u32 s54, s58, s41
	s_addc_u32 s55, s59, 0
	v_add_u32_e32 v89, s37, v89
	v_add_u32_e32 v90, s36, v89
	v_add_u32_e32 v91, s36, v90
	v_add_u32_e32 v92, s36, v91
	v_add_u32_e32 v93, s36, v92
	v_add_u32_e32 v94, s36, v93
	v_add_u32_e32 v95, s36, v94
	v_add_u32_e32 v96, s36, v95
	v_readfirstlane_b32 s36, v68
	v_readfirstlane_b32 s37, v69
	s_cmp_eq_u32 s61, 0
	s_cselect_b32 s58, 64, 0xf80
	s_mul_i32 s59, s58, 0x4800
	s_add_u32 s36, s36, s59
	s_addc_u32 s37, s37, 0
	s_lshl_b32 s59, s58, 6
	s_add_u32 s38, s8, s59
	s_addc_u32 s39, s9, 0
	s_xor_b32 s40, s57, 0x120000
	s_sub_i32 s40, s40, s57
	s_xor_b32 s41, s57, 0x1000
	s_sub_i32 s41, s41, s57
	s_and_b32 s58, s57, 64
	s_xor_b32 s59, s57, 0x4800
	s_sub_i32 s59, s59, s57
	s_xor_b32 s60, s57, 64
	s_sub_i32 s60, s60, s57
	v_xor_b32_e32 v73, s57, v182
	v_add_u32_e32 v73, s58, v73
	v_mul_u32_u24_e32 v97, 0x4800, v73
	v_lshl_add_u32 v97, v50, 2, v97
	v_lshlrev_b32_e32 v50, 6, v73
	v_add_u32_e32 v98, s59, v97
	v_add_u32_e32 v99, s59, v98
	v_add_u32_e32 v100, s59, v99
	v_add_u32_e32 v101, s59, v100
	v_add_u32_e32 v102, s59, v101
	v_add_u32_e32 v103, s59, v102
	v_add_u32_e32 v104, s59, v103
	v_add_u32_e32 v51, s60, v50
	v_add_u32_e32 v52, s60, v51
	v_add_u32_e32 v53, s60, v52
	v_add_u32_e32 v54, s60, v53
	v_add_u32_e32 v55, s60, v54
	v_add_u32_e32 v56, s60, v55
	v_add_u32_e32 v57, s60, v56
	v_xor_b32_e32 v73, s57, v220
	v_add_u32_e32 v73, s58, v73
	v_lshlrev_b32_e32 v73, 6, v73
	v_lshrrev_b32_e32 v59, 1, v220
	s_lshr_b32 s58, s35, 6
	s_and_b32 s58, s58, 1
	s_lshl_b32 s58, s58, 5
	s_and_b32 s59, s57, 64
	v_add_u32_e32 v59, s58, v59
	v_xor_b32_e32 v59, s57, v59
	v_add_u32_e32 v59, s59, v59
	v_mul_u32_u24_e32 v59, 0x4800, v59
	v_and_b32_e32 v58, 1, v220
	v_lshl_add_u32 v59, v58, 5, v59
	s_waitcnt vmcnt(32)
	s_branch .LBB0_453

.LBB0_457:
	s_add_i32 s27, s19, -2
	s_cmp_lt_u32 s27, 62
	s_cselect_b64 s[14:15], -1, 0
.LBB0_459:
	s_and_b64 vcc, exec, s[6:7]
	s_cbranch_vccnz .LBB0_461
	global_load_dword v2, v97, s[36:37] nt
	global_load_dword v10, v50, s[38:39]
	global_load_dword v3, v98, s[36:37] nt
	global_load_dword v11, v51, s[38:39]
	global_load_dword v4, v99, s[36:37] nt
	global_load_dword v12, v52, s[38:39]
	global_load_dword v5, v100, s[36:37] nt
	global_load_dword v13, v53, s[38:39]
	global_load_dword v6, v101, s[36:37] nt
	global_load_dword v14, v54, s[38:39]
	global_load_dword v7, v102, s[36:37] nt
	global_load_dword v15, v55, s[38:39]
	global_load_dword v8, v103, s[36:37] nt
	global_load_dword v16, v56, s[38:39]
	global_load_dword v9, v104, s[36:37] nt
	global_load_dword v17, v57, s[38:39]
	s_add_u32 s58, s36, s40
	s_addc_u32 s59, s37, s57
	global_load_dword v58, v59, s[58:59]

.LBB0_463:
	global_load_dword v207, v73, s[38:39] offset:32
	s_add_u32 s36, s36, s40
	s_addc_u32 s37, s37, s57
	s_add_u32 s38, s38, s41
	s_addc_u32 s39, s39, s57
	s_waitcnt lgkmcnt(0)
	s_barrier
	ds_read_b128 v[226:229], v187
	v_add_u32_e32 v46, v79, v167
	ds_read_b128 v[230:233], v46
	ds_read_b128 v[234:237], v80
	s_waitcnt lgkmcnt(1)
	v_mfma_f32_16x16x32_bf16 v[230:233], v[226:229], v[230:233], 0
	global_load_dword v113, v89, s[52:53]
	s_waitcnt lgkmcnt(0)
	v_mfma_f32_16x16x32_bf16 v[226:229], v[226:229], v[234:237], 0
	global_load_dword v114, v89, s[52:53] offset:2048
	ds_read_b128 v[234:237], v187 offset:64
	ds_read_b128 v[238:241], v46 offset:64
	s_waitcnt lgkmcnt(0)
	v_mfma_f32_16x16x32_bf16 v[230:233], v[234:237], v[238:241], v[230:233]
	global_load_dword v115, v89, s[54:55]
	ds_read_b128 v[238:241], v80 offset:64
	s_waitcnt lgkmcnt(0)
	v_mfma_f32_16x16x32_bf16 v[226:229], v[234:237], v[238:241], v[226:229]
	global_load_dword v116, v89, s[54:55] offset:2048
	ds_read_b128 v[234:237], v187 offset:128
	ds_read_b128 v[238:241], v46 offset:128
	s_waitcnt lgkmcnt(0)
	v_mfma_f32_16x16x32_bf16 v[230:233], v[234:237], v[238:241], v[230:233]
	global_load_dword v117, v90, s[52:53]
	ds_read_b128 v[238:241], v80 offset:128
	s_waitcnt lgkmcnt(0)
	v_mfma_f32_16x16x32_bf16 v[226:229], v[234:237], v[238:241], v[226:229]
	global_load_dword v118, v90, s[52:53] offset:2048
	ds_read_b128 v[234:237], v187 offset:192
	ds_read_b128 v[238:241], v46 offset:192
	s_waitcnt lgkmcnt(0)
	v_mfma_f32_16x16x32_bf16 v[230:233], v[234:237], v[238:241], v[230:233]
	global_load_dword v119, v90, s[54:55]
	ds_read_b128 v[238:241], v80 offset:192
	s_waitcnt lgkmcnt(0)
	v_mfma_f32_16x16x32_bf16 v[226:229], v[234:237], v[238:241], v[226:229]
	global_load_dword v120, v90, s[54:55] offset:2048
	ds_read_b128 v[234:237], v187 offset:256
	ds_read_b128 v[238:241], v46 offset:256
	s_waitcnt lgkmcnt(0)
	v_mfma_f32_16x16x32_bf16 v[230:233], v[234:237], v[238:241], v[230:233]
	global_load_dword v121, v91, s[52:53]
	ds_read_b128 v[238:241], v80 offset:256
	s_waitcnt lgkmcnt(0)
	v_mfma_f32_16x16x32_bf16 v[226:229], v[234:237], v[238:241], v[226:229]
	global_load_dword v122, v91, s[52:53] offset:2048
	ds_read_b128 v[234:237], v187 offset:320
	ds_read_b128 v[238:241], v46 offset:320
	s_waitcnt lgkmcnt(0)
	v_mfma_f32_16x16x32_bf16 v[230:233], v[234:237], v[238:241], v[230:233]
	global_load_dword v123, v91, s[54:55]
	ds_read_b128 v[238:241], v80 offset:320
	s_waitcnt lgkmcnt(0)
	v_mfma_f32_16x16x32_bf16 v[226:229], v[234:237], v[238:241], v[226:229]
	global_load_dword v124, v91, s[54:55] offset:2048
	ds_read_b128 v[234:237], v187 offset:384
	ds_read_b128 v[238:241], v46 offset:384
	s_waitcnt lgkmcnt(0)
	v_mfma_f32_16x16x32_bf16 v[230:233], v[234:237], v[238:241], v[230:233]
	global_load_dword v125, v92, s[52:53]
	ds_read_b128 v[238:241], v80 offset:384
	s_waitcnt lgkmcnt(0)
	v_mfma_f32_16x16x32_bf16 v[226:229], v[234:237], v[238:241], v[226:229]
	global_load_dword v126, v92, s[52:53] offset:2048
	ds_read_b128 v[234:237], v187 offset:448
	ds_read_b128 v[238:241], v46 offset:448
	s_waitcnt lgkmcnt(0)
	v_mfma_f32_16x16x32_bf16 v[230:233], v[234:237], v[238:241], v[230:233]
	global_load_dword v134, v92, s[54:55]
	ds_read_b128 v[238:241], v80 offset:448
	s_waitcnt lgkmcnt(0)
	v_mfma_f32_16x16x32_bf16 v[226:229], v[234:237], v[238:241], v[226:229]
	global_load_dword v135, v92, s[54:55] offset:2048
	ds_bpermute_b32 v46, v176, v48
	v_add_u32_e32 v206, v77, v75
	v_add_u32_e32 v217, s18, v183
	s_waitcnt lgkmcnt(0)
	v_mul_f32_e32 v46, 0x3fb8aa3b, v46
	v_exp_f32_e32 v218, v46
	ds_bpermute_b32 v46, v177, v48
	s_waitcnt lgkmcnt(0)
	v_mul_f32_e32 v46, 0x3fb8aa3b, v46
	v_exp_f32_e32 v219, v46
	ds_bpermute_b32 v46, v178, v48
	v_pk_mul_f32 v[226:227], v[226:227], v[218:219]
	s_waitcnt lgkmcnt(0)
	v_mul_f32_e32 v46, 0x3fb8aa3b, v46
	v_exp_f32_e32 v222, v46
	ds_bpermute_b32 v46, v179, v48
	s_waitcnt lgkmcnt(0)
	v_mul_f32_e32 v46, 0x3fb8aa3b, v46
	v_exp_f32_e32 v223, v46
	v_pk_mul_f32 v[46:47], v[230:231], v[218:219]
	v_add_u32_e32 v218, v168, v81
	ds_read_b128 v[234:237], v218
	v_pk_mul_f32 v[48:49], v[232:233], v[222:223]
	ds_read_b128 v[230:233], v188
	v_pk_mul_f32 v[228:229], v[228:229], v[222:223]
	v_add_u32_e32 v219, v168, v82
	v_add_u32_e32 v222, s26, v185
	s_waitcnt lgkmcnt(0)
	v_mfma_f32_16x16x32_bf16 v[46:49], v[230:233], v[234:237], v[46:49]
	global_load_dword v136, v93, s[52:53]
	ds_read_b128 v[234:237], v206
	s_waitcnt lgkmcnt(0)
	v_mfma_f32_16x16x32_bf16 v[226:229], v[230:233], v[234:237], v[226:229]
	global_load_dword v137, v93, s[52:53] offset:2048
	ds_read_b128 v[230:233], v188 offset:64
	ds_read_b128 v[234:237], v219
	s_waitcnt lgkmcnt(0)
	v_mfma_f32_16x16x32_bf16 v[46:49], v[230:233], v[234:237], v[46:49]
	global_load_dword v138, v93, s[54:55]
	ds_read_b128 v[234:237], v110
	s_waitcnt lgkmcnt(0)
	v_mfma_f32_16x16x32_bf16 v[226:229], v[230:233], v[234:237], v[226:229]
	global_load_dword v139, v93, s[54:55] offset:2048
	v_cndmask_b32_e64 v230, v222, v217, s[2:3]
	v_ashrrev_i32_e32 v231, 31, v230
	v_lshlrev_b64 v[230:231], 12, v[230:231]
	s_nop 4
	ds_bpermute_b32 v223, v170, v226
	v_lshl_add_u64 v[230:231], v[70:71], 0, v[230:231]
	s_waitcnt lgkmcnt(0)
	v_max_f32_e64 v223, |v223|, |v223|
	v_max_f32_e32 v223, 1.0, v223
	v_div_scale_f32 v225, s[16:17], v223, v223, v46
	v_rcp_f32_e32 v226, v225
	s_nop 0
	v_fma_f32 v232, -v225, v226, 1.0
	v_fmac_f32_e32 v226, v232, v226
	v_div_scale_f32 v232, vcc, v46, v223, v46
	v_mul_f32_e32 v233, v232, v226
	v_fma_f32 v234, -v225, v233, v232
	v_fmac_f32_e32 v233, v234, v226
	v_fma_f32 v225, -v225, v233, v232
	v_div_fmas_f32 v225, v225, v226, v233
	v_div_fixup_f32 v46, v225, v223, v46
	v_cvt_pk_bf16_f32 v46, v46, s0
	global_store_short v[230:231], v46, off offset:2048
	ds_bpermute_b32 v46, v170, v227
	v_add_u32_e32 v223, -1, v222
	v_add_u32_e32 v225, 1, v217
	v_cndmask_b32_e64 v226, v223, v225, s[2:3]
	v_ashrrev_i32_e32 v227, 31, v226
	s_waitcnt lgkmcnt(0)
	v_max_f32_e64 v46, |v46|, |v46|
	v_max_f32_e32 v46, 1.0, v46
	v_div_scale_f32 v223, s[16:17], v46, v46, v47
	v_rcp_f32_e32 v225, v223
	s_nop 0
	v_fma_f32 v230, -v223, v225, 1.0
	v_fmac_f32_e32 v225, v230, v225
	v_div_scale_f32 v230, vcc, v47, v46, v47
	v_mul_f32_e32 v231, v230, v225
	v_fma_f32 v232, -v223, v231, v230
	v_fmac_f32_e32 v231, v232, v225
	v_fma_f32 v223, -v223, v231, v230
	v_div_fmas_f32 v223, v223, v225, v231
	ds_bpermute_b32 v225, v170, v228
	v_div_fixup_f32 v46, v223, v46, v47
	v_cvt_pk_bf16_f32 v223, v46, s0
	v_lshlrev_b64 v[46:47], 12, v[226:227]
	v_lshl_add_u64 v[46:47], v[70:71], 0, v[46:47]
	s_waitcnt lgkmcnt(0)
	v_max_f32_e64 v225, |v225|, |v225|
	v_max_f32_e32 v225, 1.0, v225
	v_div_scale_f32 v226, s[16:17], v225, v225, v48
	v_rcp_f32_e32 v227, v226
	global_store_short v[46:47], v223, off offset:2048
	v_add_u32_e32 v223, s26, v184
	v_add_u32_e32 v46, 0xffd, v223
	v_fma_f32 v228, -v226, v227, 1.0
	v_fmac_f32_e32 v227, v228, v227
	v_div_scale_f32 v228, vcc, v48, v225, v48
	v_mul_f32_e32 v230, v228, v227
	v_fma_f32 v231, -v226, v230, v228
	v_add_u32_e32 v47, 2, v217
	v_fmac_f32_e32 v230, v231, v227
	v_cndmask_b32_e64 v46, v46, v47, s[2:3]
	v_fma_f32 v226, -v226, v230, v228
	v_ashrrev_i32_e32 v47, 31, v46
	v_div_fmas_f32 v226, v226, v227, v230
	v_div_fixup_f32 v48, v226, v225, v48
	v_lshlrev_b64 v[46:47], 12, v[46:47]
	v_cvt_pk_bf16_f32 v48, v48, s0
	v_lshl_add_u64 v[46:47], v[70:71], 0, v[46:47]
	global_store_short v[46:47], v48, off offset:2048
	ds_bpermute_b32 v48, v170, v229
	v_add_u32_e32 v46, 0xffc, v223
	v_add_u32_e32 v47, 3, v217
	v_cndmask_b32_e64 v46, v46, v47, s[2:3]
	v_ashrrev_i32_e32 v47, 31, v46
	s_waitcnt lgkmcnt(0)
	v_max_f32_e64 v48, |v48|, |v48|
	v_max_f32_e32 v48, 1.0, v48
	v_div_scale_f32 v225, s[16:17], v48, v48, v49
	v_rcp_f32_e32 v226, v225
	v_lshlrev_b64 v[46:47], 12, v[46:47]
	v_lshl_add_u64 v[46:47], v[70:71], 0, v[46:47]
	v_fma_f32 v227, -v225, v226, 1.0
	v_fmac_f32_e32 v226, v227, v226
	v_div_scale_f32 v227, vcc, v49, v48, v49
	v_mul_f32_e32 v228, v227, v226
	v_fma_f32 v229, -v225, v228, v227
	v_fmac_f32_e32 v228, v229, v226
	v_fma_f32 v225, -v225, v228, v227
	v_div_fmas_f32 v225, v225, v226, v228
	v_div_fixup_f32 v48, v225, v48, v49
	v_cvt_pk_bf16_f32 v48, v48, s0
	global_store_short v[46:47], v48, off offset:2048
	v_mul_f32_e32 v46, 0x3fb8aa3b, v224
	v_add_u32_e32 v224, v0, v81
	v_exp_f32_e32 v46, v46
	ds_read_b128 v[226:229], v224 offset:33792
	ds_read_b128 v[230:233], v111
	v_add_u32_e32 v49, v0, v82
	v_add_u32_e32 v225, v84, v82
	v_pk_mul_f32 v[44:45], v[44:45], v[46:47] op_sel_hi:[1,0]
	v_pk_mul_f32 v[42:43], v[42:43], v[46:47] op_sel_hi:[1,0]
	v_pk_mul_f32 v[40:41], v[40:41], v[46:47] op_sel_hi:[1,0]
	v_pk_mul_f32 v[38:39], v[38:39], v[46:47] op_sel_hi:[1,0]
	s_waitcnt lgkmcnt(0)
	v_mfma_f32_16x16x32_bf16 v[42:45], v[226:229], v[230:233], v[42:45]
	global_load_dword v140, v94, s[52:53]
	ds_read_b128 v[226:229], v49 offset:33792
	ds_read_b128 v[230:233], v225
	v_pk_mul_f32 v[36:37], v[36:37], v[46:47] op_sel_hi:[1,0]
	s_waitcnt lgkmcnt(0)
	v_mfma_f32_16x16x32_bf16 v[42:45], v[226:229], v[230:233], v[42:45]
	global_load_dword v141, v94, s[52:53] offset:2048
	v_mul_f32_e64 v34, v34, v46
	v_mul_f32_e64 v35, v35, v46
	s_nop 5
	v_cvt_pk_bf16_f32 v226, v42, v43
	v_cvt_pk_bf16_f32 v227, v44, v45
	ds_write_b64 v189, v[226:227] offset:17952
	v_add_u32_e32 v226, v86, v81
	ds_read_b128 v[228:231], v49 offset:33792
	ds_read_b128 v[232:235], v224 offset:33792
	ds_read_b128 v[236:239], v226
	v_add_u32_e32 v227, v86, v82
	s_waitcnt lgkmcnt(0)
	v_mfma_f32_16x16x32_bf16 v[38:41], v[232:235], v[236:239], v[38:41]
	global_load_dword v142, v94, s[54:55]
	ds_read_b128 v[232:235], v227
	s_waitcnt lgkmcnt(0)
	v_mfma_f32_16x16x32_bf16 v[38:41], v[228:231], v[232:235], v[38:41]
	global_load_dword v143, v94, s[54:55] offset:2048
	s_nop 7
	v_cvt_pk_bf16_f32 v228, v38, v39
	v_cvt_pk_bf16_f32 v229, v40, v41
	ds_write_b64 v189, v[228:229] offset:26400
	ds_read_b128 v[228:231], v49 offset:33792
	ds_read_b128 v[232:235], v224 offset:33792
	ds_read_b128 v[236:239], v206
	s_waitcnt lgkmcnt(0)
	v_mfma_f32_16x16x32_bf16 v[34:37], v[232:235], v[236:239], v[34:37]
	global_load_dword v144, v95, s[52:53]
	ds_read_b128 v[232:235], v110
	s_waitcnt lgkmcnt(0)
	v_mfma_f32_16x16x32_bf16 v[34:37], v[228:231], v[232:235], v[34:37]
	global_load_dword v145, v95, s[52:53] offset:2048
	s_and_saveexec_b64 s[16:17], s[0:1]
	s_nop 6
	v_cvt_pk_bf16_f32 v228, v34, v35
	v_cvt_pk_bf16_f32 v229, v36, v37
	ds_write_b64 v172, v[228:229] offset:34848
	s_or_b64 exec, exec, s[16:17]
	ds_read_b128 v[228:231], v224 offset:36096
	ds_read_b128 v[232:235], v111
	ds_read_b128 v[236:239], v49 offset:36096
	v_mov_b32_e32 v47, v46
	v_mov_b32_e32 v240, v46
	v_mov_b32_e32 v241, v46
	v_pk_mul_f32 v[28:29], v[28:29], v[240:241]
	v_pk_mul_f32 v[26:27], v[26:27], v[46:47]
	v_pk_mul_f32 v[32:33], v[32:33], v[240:241]
	v_pk_mul_f32 v[30:31], v[30:31], v[46:47]
	s_waitcnt lgkmcnt(1)
	v_mfma_f32_16x16x32_bf16 v[26:29], v[228:231], v[232:235], v[26:29]
	global_load_dword v146, v95, s[54:55]
	ds_read_b128 v[228:231], v225
	v_pk_mul_f32 v[24:25], v[24:25], v[240:241]
	v_pk_mul_f32 v[22:23], v[22:23], v[46:47]
	s_waitcnt lgkmcnt(0)
	v_mfma_f32_16x16x32_bf16 v[26:29], v[236:239], v[228:231], v[26:29]
	global_load_dword v147, v95, s[54:55] offset:2048
	s_nop 7
	v_cvt_pk_bf16_f32 v228, v26, v27
	v_cvt_pk_bf16_f32 v229, v28, v29
	ds_write_b64 v189, v[228:229] offset:17984
	ds_read_b128 v[228:231], v224 offset:36096
	ds_read_b128 v[232:235], v226
	ds_read_b128 v[236:239], v227
	s_waitcnt lgkmcnt(1)
	v_mfma_f32_16x16x32_bf16 v[30:33], v[228:231], v[232:235], v[30:33]
	global_load_dword v149, v96, s[52:53]
	ds_read_b128 v[228:231], v49 offset:36096
	s_waitcnt lgkmcnt(0)
	v_mfma_f32_16x16x32_bf16 v[30:33], v[228:231], v[236:239], v[30:33]
	global_load_dword v150, v96, s[52:53] offset:2048
	s_nop 7
	v_cvt_pk_bf16_f32 v228, v30, v31
	v_cvt_pk_bf16_f32 v229, v32, v33
	ds_write_b64 v189, v[228:229] offset:26432
	ds_read_b128 v[228:231], v224 offset:36096
	ds_read_b128 v[232:235], v206
	ds_read_b128 v[236:239], v110
	s_waitcnt lgkmcnt(1)
	v_mfma_f32_16x16x32_bf16 v[22:25], v[228:231], v[232:235], v[22:25]
	global_load_dword v155, v96, s[54:55]
	ds_read_b128 v[228:231], v49 offset:36096
	s_waitcnt lgkmcnt(0)
	v_mfma_f32_16x16x32_bf16 v[22:25], v[228:231], v[236:239], v[22:25]
	global_load_dword v156, v96, s[54:55] offset:2048
	s_add_u32 s52, s52, s56
	s_addc_u32 s53, s53, s57
	s_add_u32 s54, s54, s56
	s_addc_u32 s55, s55, s57
	s_and_saveexec_b64 s[16:17], s[0:1]
	s_nop 6
	v_cvt_pk_bf16_f32 v46, v22, v23
	v_cvt_pk_bf16_f32 v47, v24, v25
	ds_write_b64 v172, v[46:47] offset:34880
	s_or_b64 exec, exec, s[16:17]
	s_waitcnt vmcnt(36)
	ds_bpermute_b32 v228, v109, v207
	s_waitcnt lgkmcnt(0)
	s_barrier
	s_and_b64 vcc, exec, s[4:5]
	s_cbranch_vccnz .LBB0_469
	v_cvt_pk_bf16_f32 v46, v148, s0
	ds_write_b16 v72, v46 offset:4608

.LBB0_471:
.LBB0_473:
	s_cmp_gt_u32 s28, 62
	s_cbranch_scc1 .LBB0_479
	s_and_b64 vcc, exec, s[6:7]
	s_xor_b32 s6, s18, 0xffffff80
	s_cbranch_vccnz .LBB0_476
	global_load_dword v2, v97, s[36:37] nt
	global_load_dword v10, v50, s[38:39]
	global_load_dword v3, v98, s[36:37] nt
	global_load_dword v11, v51, s[38:39]
	global_load_dword v4, v99, s[36:37] nt
	global_load_dword v12, v52, s[38:39]
	global_load_dword v5, v100, s[36:37] nt
	global_load_dword v13, v53, s[38:39]
	global_load_dword v6, v101, s[36:37] nt
	global_load_dword v14, v54, s[38:39]
	global_load_dword v7, v102, s[36:37] nt
	global_load_dword v15, v55, s[38:39]
	global_load_dword v8, v103, s[36:37] nt
	global_load_dword v16, v56, s[38:39]
	global_load_dword v9, v104, s[36:37] nt
	global_load_dword v17, v57, s[38:39]
	s_add_u32 s58, s36, s40
	s_addc_u32 s59, s37, s57
	global_load_dword v58, v59, s[58:59]

.LBB0_480:
	s_waitcnt lgkmcnt(0)
	s_barrier
	ds_read_b128 v[208:211], v187
	v_add_u32_e32 v46, v87, v167
	ds_read_b128 v[212:215], v46
	ds_read_b128 v[230:233], v187 offset:64
	ds_read_b128 v[234:237], v46 offset:64
	ds_read_b128 v[238:241], v88
	ds_read_b128 v[242:245], v88 offset:64
	s_waitcnt lgkmcnt(4)
	v_mfma_f32_16x16x32_bf16 v[212:215], v[208:211], v[212:215], 0
	global_load_dword v151, v89, s[52:53]
	s_waitcnt lgkmcnt(1)
	v_mfma_f32_16x16x32_bf16 v[208:211], v[208:211], v[238:241], 0
	global_load_dword v152, v89, s[52:53] offset:2048
	v_mfma_f32_16x16x32_bf16 v[212:215], v[230:233], v[234:237], v[212:215]
	global_load_dword v153, v89, s[54:55]
	s_waitcnt lgkmcnt(0)
	v_mfma_f32_16x16x32_bf16 v[208:211], v[230:233], v[242:245], v[208:211]
	global_load_dword v154, v89, s[54:55] offset:2048
	ds_read_b128 v[230:233], v187 offset:128
	ds_read_b128 v[234:237], v46 offset:128
	ds_read_b128 v[238:241], v46 offset:192
	ds_read_b128 v[242:245], v187 offset:192
	s_waitcnt lgkmcnt(2)
	v_mfma_f32_16x16x32_bf16 v[212:215], v[230:233], v[234:237], v[212:215]
	global_load_dword v157, v90, s[52:53]
	ds_read_b128 v[234:237], v88 offset:128
	ds_read_b128 v[246:249], v88 offset:192
	s_waitcnt lgkmcnt(1)
	v_mfma_f32_16x16x32_bf16 v[208:211], v[230:233], v[234:237], v[208:211]
	global_load_dword v158, v90, s[52:53] offset:2048
	v_mfma_f32_16x16x32_bf16 v[212:215], v[242:245], v[238:241], v[212:215]
	global_load_dword v159, v90, s[54:55]
	s_waitcnt lgkmcnt(0)
	v_mfma_f32_16x16x32_bf16 v[208:211], v[242:245], v[246:249], v[208:211]
	global_load_dword v160, v90, s[54:55] offset:2048
	ds_read_b128 v[230:233], v187 offset:256
	ds_read_b128 v[234:237], v46 offset:256
	ds_read_b128 v[238:241], v46 offset:320
	ds_read_b128 v[242:245], v187 offset:320
	s_waitcnt lgkmcnt(2)
	v_mfma_f32_16x16x32_bf16 v[212:215], v[230:233], v[234:237], v[212:215]
	global_load_dword v161, v91, s[52:53]
	ds_read_b128 v[234:237], v88 offset:256
	ds_read_b128 v[246:249], v88 offset:320
	s_waitcnt lgkmcnt(1)
	v_mfma_f32_16x16x32_bf16 v[208:211], v[230:233], v[234:237], v[208:211]
	global_load_dword v162, v91, s[52:53] offset:2048
	v_mfma_f32_16x16x32_bf16 v[212:215], v[242:245], v[238:241], v[212:215]
	global_load_dword v164, v91, s[54:55]
	s_waitcnt lgkmcnt(0)
	v_mfma_f32_16x16x32_bf16 v[208:211], v[242:245], v[246:249], v[208:211]
	global_load_dword v165, v91, s[54:55] offset:2048
	ds_read_b128 v[230:233], v187 offset:384
	ds_read_b128 v[234:237], v46 offset:384
	ds_read_b128 v[238:241], v46 offset:448
	ds_read_b128 v[242:245], v187 offset:448
	s_waitcnt lgkmcnt(2)
	v_mfma_f32_16x16x32_bf16 v[212:215], v[230:233], v[234:237], v[212:215]
	global_load_dword v169, v92, s[52:53]
	ds_read_b128 v[234:237], v88 offset:384
	ds_read_b128 v[246:249], v88 offset:448
	s_waitcnt lgkmcnt(1)
	v_mfma_f32_16x16x32_bf16 v[208:211], v[230:233], v[234:237], v[208:211]
	global_load_dword v171, v92, s[52:53] offset:2048
	v_mfma_f32_16x16x32_bf16 v[212:215], v[242:245], v[238:241], v[212:215]
	global_load_dword v180, v92, s[54:55]
	s_waitcnt lgkmcnt(0)
	v_mfma_f32_16x16x32_bf16 v[208:211], v[242:245], v[246:249], v[208:211]
	global_load_dword v181, v92, s[54:55] offset:2048
	ds_bpermute_b32 v46, v176, v207
	ds_bpermute_b32 v47, v177, v207
	ds_bpermute_b32 v216, v178, v207
	ds_bpermute_b32 v207, v179, v207
	ds_read_b128 v[230:233], v188
	ds_read_b128 v[234:237], v218
	s_waitcnt lgkmcnt(5)
	v_mul_f32_e32 v46, 0x3fb8aa3b, v46
	s_waitcnt lgkmcnt(4)
	v_mul_f32_e32 v47, 0x3fb8aa3b, v47
	s_waitcnt lgkmcnt(3)
	v_mul_f32_e32 v216, 0x3fb8aa3b, v216
	s_waitcnt lgkmcnt(2)
	v_mul_f32_e32 v207, 0x3fb8aa3b, v207
	v_exp_f32_e32 v46, v46
	v_exp_f32_e32 v47, v47
	v_exp_f32_e32 v246, v216
	v_exp_f32_e32 v247, v207
	ds_read_b128 v[238:241], v206
	ds_read_b128 v[242:245], v188 offset:64
	v_pk_mul_f32 v[212:213], v[212:213], v[46:47]
	v_pk_mul_f32 v[208:209], v[208:209], v[46:47]
	v_pk_mul_f32 v[214:215], v[214:215], v[246:247]
	v_pk_mul_f32 v[210:211], v[210:211], v[246:247]
	v_add_u32_e32 v47, 64, v217
	s_waitcnt lgkmcnt(2)
	v_mfma_f32_16x16x32_bf16 v[212:215], v[230:233], v[234:237], v[212:215]
	global_load_dword v190, v93, s[52:53]
	s_waitcnt lgkmcnt(1)
	v_mfma_f32_16x16x32_bf16 v[208:211], v[230:233], v[238:241], v[208:211]
	global_load_dword v191, v93, s[52:53] offset:2048
	ds_read_b128 v[230:233], v110
	ds_read_b128 v[234:237], v219
	s_waitcnt lgkmcnt(1)
	v_mfma_f32_16x16x32_bf16 v[208:211], v[242:245], v[230:233], v[208:211]
	global_load_dword v192, v93, s[54:55]
	s_waitcnt lgkmcnt(0)
	v_mfma_f32_16x16x32_bf16 v[212:215], v[242:245], v[234:237], v[212:215]
	global_load_dword v193, v93, s[54:55] offset:2048
	s_nop 5
	ds_bpermute_b32 v46, v170, v208
	s_waitcnt lgkmcnt(0)
	v_max_f32_e64 v46, |v46|, |v46|
	v_max_f32_e32 v207, 1.0, v46
	v_div_scale_f32 v208, s[4:5], v207, v207, v212
	v_rcp_f32_e32 v216, v208
	v_subrev_u32_e32 v46, 64, v222
	v_cndmask_b32_e64 v46, v46, v47, s[2:3]
	v_ashrrev_i32_e32 v47, 31, v46
	v_fma_f32 v218, -v208, v216, 1.0
	v_fmac_f32_e32 v216, v218, v216
	v_div_scale_f32 v218, vcc, v212, v207, v212
	v_mul_f32_e32 v219, v218, v216
	v_fma_f32 v229, -v208, v219, v218
	v_fmac_f32_e32 v219, v229, v216
	v_fma_f32 v208, -v208, v219, v218
	v_div_fmas_f32 v208, v208, v216, v219
	v_div_fixup_f32 v207, v208, v207, v212
	ds_bpermute_b32 v208, v170, v209
	v_lshlrev_b64 v[46:47], 12, v[46:47]
	v_cvt_pk_bf16_f32 v207, v207, s0
	v_lshl_add_u64 v[46:47], v[70:71], 0, v[46:47]
	global_store_short v[46:47], v207, off offset:2048
	s_waitcnt lgkmcnt(0)
	v_max_f32_e64 v47, |v208|, |v208|
	v_max_f32_e32 v207, 1.0, v47
	v_div_scale_f32 v208, s[4:5], v207, v207, v213
	v_rcp_f32_e32 v209, v208
	v_add_u32_e32 v46, 0xffffffbf, v222
	v_add_u32_e32 v47, 0x41, v217
	v_cndmask_b32_e64 v46, v46, v47, s[2:3]
	v_fma_f32 v212, -v208, v209, 1.0
	v_fmac_f32_e32 v209, v212, v209
	v_div_scale_f32 v212, vcc, v213, v207, v213
	v_mul_f32_e32 v216, v212, v209
	v_fma_f32 v218, -v208, v216, v212
	v_fmac_f32_e32 v216, v218, v209
	v_fma_f32 v208, -v208, v216, v212
	v_div_fmas_f32 v208, v208, v209, v216
	v_div_fixup_f32 v207, v208, v207, v213
	ds_bpermute_b32 v208, v170, v210
	v_ashrrev_i32_e32 v47, 31, v46
	v_lshlrev_b64 v[46:47], 12, v[46:47]
	v_cvt_pk_bf16_f32 v207, v207, s0
	v_lshl_add_u64 v[46:47], v[70:71], 0, v[46:47]
	global_store_short v[46:47], v207, off offset:2048
	s_waitcnt lgkmcnt(0)
	v_max_f32_e64 v47, |v208|, |v208|
	v_max_f32_e32 v207, 1.0, v47
	v_div_scale_f32 v208, s[4:5], v207, v207, v214
	v_rcp_f32_e32 v209, v208
	v_add_u32_e32 v46, 0xfbd, v223
	v_add_u32_e32 v47, 0x42, v217
	v_cndmask_b32_e64 v46, v46, v47, s[2:3]
	v_fma_f32 v210, -v208, v209, 1.0
	v_fmac_f32_e32 v209, v210, v209
	v_div_scale_f32 v210, vcc, v214, v207, v214
	v_mul_f32_e32 v212, v210, v209
	v_fma_f32 v213, -v208, v212, v210
	v_fmac_f32_e32 v212, v213, v209
	v_fma_f32 v208, -v208, v212, v210
	v_div_fmas_f32 v208, v208, v209, v212
	v_div_fixup_f32 v207, v208, v207, v214
	ds_bpermute_b32 v208, v170, v211
	v_ashrrev_i32_e32 v47, 31, v46
	v_lshlrev_b64 v[46:47], 12, v[46:47]
	v_cvt_pk_bf16_f32 v207, v207, s0
	v_lshl_add_u64 v[46:47], v[70:71], 0, v[46:47]
	global_store_short v[46:47], v207, off offset:2048
	s_waitcnt lgkmcnt(0)
	v_max_f32_e64 v46, |v208|, |v208|
	ds_read_b128 v[208:211], v224 offset:33792
	v_max_f32_e32 v212, 1.0, v46
	v_mul_f32_e32 v46, 0x3fb8aa3b, v228
	v_exp_f32_e32 v46, v46
	v_add_u32_e32 v207, 0x43, v217
	ds_read_b128 v[216:219], v111
	ds_read_b128 v[228:231], v49 offset:33792
	v_add_u32_e32 v47, 0xfbc, v223
	v_pk_mul_f32 v[44:45], v[44:45], v[46:47] op_sel_hi:[1,0]
	v_pk_mul_f32 v[42:43], v[42:43], v[46:47] op_sel_hi:[1,0]
	ds_read_b128 v[232:235], v225
	v_div_scale_f32 v213, s[4:5], v212, v212, v215
	s_waitcnt lgkmcnt(2)
	v_mfma_f32_16x16x32_bf16 v[42:45], v[208:211], v[216:219], v[42:45]
	global_load_dword v194, v94, s[52:53]
	v_rcp_f32_e32 v214, v213
	v_cndmask_b32_e64 v222, v47, v207, s[2:3]
	v_ashrrev_i32_e32 v223, 31, v222
	s_waitcnt lgkmcnt(0)
	v_mfma_f32_16x16x32_bf16 v[42:45], v[228:231], v[232:235], v[42:45]
	global_load_dword v195, v94, s[52:53] offset:2048
	v_fma_f32 v47, -v213, v214, 1.0
	v_fmac_f32_e32 v214, v47, v214
	v_div_scale_f32 v47, vcc, v215, v212, v215
	v_pk_mul_f32 v[40:41], v[40:41], v[46:47] op_sel_hi:[1,0]
	s_nop 3
	v_cvt_pk_bf16_f32 v208, v42, v43
	v_cvt_pk_bf16_f32 v209, v44, v45
	ds_write_b64 v189, v[208:209]
	ds_read_b128 v[208:211], v49 offset:33792
	ds_read_b128 v[216:219], v224 offset:33792
	ds_read_b128 v[228:231], v226
	ds_read_b128 v[232:235], v227
	v_pk_mul_f32 v[38:39], v[38:39], v[46:47] op_sel_hi:[1,0]
	v_mul_f32_e32 v207, v47, v214
	s_waitcnt lgkmcnt(1)
	v_mfma_f32_16x16x32_bf16 v[38:41], v[216:219], v[228:231], v[38:41]
	global_load_dword v196, v94, s[54:55]
	v_fma_f32 v216, -v213, v207, v47
	v_fmac_f32_e32 v207, v216, v214
	v_fma_f32 v47, -v213, v207, v47
	s_waitcnt lgkmcnt(0)
	v_mfma_f32_16x16x32_bf16 v[38:41], v[208:211], v[232:235], v[38:41]
	global_load_dword v197, v94, s[54:55] offset:2048
	v_div_fmas_f32 v47, v47, v214, v207
	v_div_fixup_f32 v47, v47, v212, v215
	v_cvt_pk_bf16_f32 v47, v47, s0
	v_pk_mul_f32 v[36:37], v[36:37], v[46:47] op_sel_hi:[1,0]
	v_pk_mul_f32 v[34:35], v[34:35], v[46:47] op_sel_hi:[1,0]
	s_nop 2
	v_cvt_pk_bf16_f32 v208, v38, v39
	v_cvt_pk_bf16_f32 v209, v40, v41
	ds_write_b64 v189, v[208:209] offset:8448
	ds_read_b128 v[208:211], v49 offset:33792
	ds_read_b128 v[216:219], v224 offset:33792
	ds_read_b128 v[212:215], v206
	ds_read_b128 v[228:231], v110
	s_waitcnt lgkmcnt(1)
	v_mfma_f32_16x16x32_bf16 v[34:37], v[216:219], v[212:215], v[34:37]
	global_load_dword v198, v95, s[52:53]
	v_lshlrev_b64 v[212:213], 12, v[222:223]
	v_lshl_add_u64 v[212:213], v[70:71], 0, v[212:213]
	global_store_short v[212:213], v47, off offset:2048
	s_waitcnt lgkmcnt(0)
	v_mfma_f32_16x16x32_bf16 v[34:37], v[208:211], v[228:231], v[34:37]
	global_load_dword v199, v95, s[52:53] offset:2048
	s_and_saveexec_b64 s[4:5], s[0:1]
	s_nop 6
	v_cvt_pk_bf16_f32 v208, v34, v35
	v_cvt_pk_bf16_f32 v209, v36, v37
	ds_write_b64 v172, v[208:209] offset:16896
	s_or_b64 exec, exec, s[4:5]
	ds_read_b128 v[208:211], v224 offset:36096
	ds_read_b128 v[212:215], v111
	ds_read_b128 v[216:219], v49 offset:36096
	v_mov_b32_e32 v47, v46
	v_mov_b32_e32 v222, v46
	v_mov_b32_e32 v223, v46
	v_pk_mul_f32 v[28:29], v[28:29], v[222:223]
	v_pk_mul_f32 v[26:27], v[26:27], v[46:47]
	v_pk_mul_f32 v[32:33], v[32:33], v[222:223]
	v_pk_mul_f32 v[30:31], v[30:31], v[46:47]
	s_waitcnt lgkmcnt(1)
	v_mfma_f32_16x16x32_bf16 v[26:29], v[208:211], v[212:215], v[26:29]
	global_load_dword v200, v95, s[54:55]
	ds_read_b128 v[208:211], v225
	v_pk_mul_f32 v[24:25], v[24:25], v[222:223]
	v_pk_mul_f32 v[22:23], v[22:23], v[46:47]
	s_waitcnt lgkmcnt(0)
	v_mfma_f32_16x16x32_bf16 v[26:29], v[216:219], v[208:211], v[26:29]
	global_load_dword v201, v95, s[54:55] offset:2048
	s_nop 7
	v_cvt_pk_bf16_f32 v208, v26, v27
	v_cvt_pk_bf16_f32 v209, v28, v29
	ds_write_b64 v189, v[208:209] offset:32
	ds_read_b128 v[208:211], v224 offset:36096
	ds_read_b128 v[212:215], v226
	ds_read_b128 v[216:219], v49 offset:36096
	ds_read_b128 v[226:229], v227
	s_waitcnt lgkmcnt(2)
	v_mfma_f32_16x16x32_bf16 v[30:33], v[208:211], v[212:215], v[30:33]
	global_load_dword v202, v96, s[52:53]
	s_waitcnt lgkmcnt(0)
	v_mfma_f32_16x16x32_bf16 v[30:33], v[216:219], v[226:229], v[30:33]
	global_load_dword v203, v96, s[52:53] offset:2048
	s_nop 7
	v_cvt_pk_bf16_f32 v208, v30, v31
	v_cvt_pk_bf16_f32 v209, v32, v33
	ds_write_b64 v189, v[208:209] offset:8480
	ds_read_b128 v[208:211], v224 offset:36096
	ds_read_b128 v[212:215], v206
	ds_read_b128 v[216:219], v49 offset:36096
	ds_read_b128 v[222:225], v110
	s_waitcnt lgkmcnt(2)
	v_mfma_f32_16x16x32_bf16 v[22:25], v[208:211], v[212:215], v[22:25]
	global_load_dword v204, v96, s[54:55]
	s_waitcnt lgkmcnt(0)
	v_mfma_f32_16x16x32_bf16 v[22:25], v[216:219], v[222:225], v[22:25]
	global_load_dword v205, v96, s[54:55] offset:2048
	s_add_u32 s52, s52, s56
	s_addc_u32 s53, s53, s57
	s_add_u32 s54, s54, s56
	s_addc_u32 s55, s55, s57
	s_and_saveexec_b64 s[4:5], s[0:1]
	s_cbranch_execz .LBB0_452
	s_nop 5
	v_cvt_pk_bf16_f32 v46, v22, v23
	v_cvt_pk_bf16_f32 v47, v24, v25
	ds_write_b64 v172, v[46:47] offset:16928
	s_branch .LBB0_452
